# cmp loop overlap weights: alternate two register quads for the second importance MFMA so no operand of an in-flight MFMA is rewritten soon after issue
# baseline (speedup 1.0000x reference)
; #define LAS __attribute__((address_space(3)))
; #define LDS_WAIT() asm volatile("s_waitcnt lgkmcnt(0)" ::: "memory")
; #define MFMA32(a, b, c) __builtin_amdgcn_mfma_f32_32x32x16_bf16((a), (b), (c), 0, 0, 0)
; DI s16x4 vtr(const LAS unsigned char* p) { return __builtin_bit_cast(s16x4, __builtin_amdgcn_ds_read_tr16_b64_v4i16((LAS v4i16_t*)p)); }
; DI bf16x8 cat8(s16x4 lo, s16x4 hi) { return __builtin_shufflevector(lo, hi, 0, 1, 2, 3, 4, 5, 6, 7); }
; template <bool CMP> DI void tile_compute(LAS unsigned char* lds, int buf, const bf16x8 (&q)[4], int lo, int hv, ASt& st, f32x16& imp0, f32x16& imp1, int jt, LAS float* wsf, int lane) {
;     ...
;     const float msub = (!anyPart && dead) ? 1e30f : mnew;
; #pragma unroll
;     for (int rg = 0; rg < 16; ++rg) { p0[rg] = __builtin_amdgcn_exp2f(p0[rg] - msub); p1[rg] = __builtin_amdgcn_exp2f(p1[rg] - msub); sum += p0[rg] + p1[rg]; }
;     st.l = st.l * alpha + sum;
;     if (__builtin_amdgcn_ballot_w64(alpha != 1.f) != 0ull) {
;         if (hi == 0) wsf[r] = alpha;
;         LDS_WAIT();
; #pragma unroll
;         for (int g4 = 0; g4 < 4; ++g4) { const f32x4 f = *(const LAS f32x4*)(wsf + 8 * g4 + 4 * hi);
; #pragma unroll
;             for (int k = 0; k < 4; ++k) { st.o0[4 * g4 + k] *= f[k]; st.o1[4 * g4 + k] *= f[k]; if (CMP) { imp0[4 * g4 + k] *= f[k]; imp1[4 * g4 + k] *= f[k]; } } }
;         LDS_WAIT();
;     }
;     bf16x8 pa[4];
;     pa[0] = pack8(p0[0], p0[1], p0[2], p0[3], p0[4], p0[5], p0[6], p0[7]); pa[1] = pack8(p0[8], p0[9], p0[10], p0[11], p0[12], p0[13], p0[14], p0[15]);
;     pa[2] = pack8(p1[0], p1[1], p1[2], p1[3], p1[4], p1[5], p1[6], p1[7]); pa[3] = pack8(p1[8], p1[9], p1[10], p1[11], p1[12], p1[13], p1[14], p1[15]);
;     const LAS unsigned char* vb = lds + A_VT + buf * 8192 + (4 * hi + ((lane & 15) >> 2)) * 64 + ((lane >> 4) & 1) * 32 + (lane & 3) * 8;
; #pragma unroll
;     for (int s = 0; s < 4; ++s) {
;         const bf16x8 v0 = cat8(vtr(vb + s * 1024), vtr(vb + s * 1024 + 512));
;         const bf16x8 v1 = cat8(vtr(vb + 4096 + s * 1024), vtr(vb + 4096 + s * 1024 + 512));
;         st.o0 = MFMA32(pa[s], v0, st.o0); st.o1 = MFMA32(pa[s], v1, st.o1);
;     }
.LBB0_555:
	v_cndmask_b32_e64 v234, v141, v223, s[78:79]
	v_sub_f32_e32 v84, v84, v234
	v_sub_f32_e32 v68, v68, v234
	v_exp_f32_e32 v235, v84
	v_exp_f32_e32 v68, v68
	v_sub_f32_e32 v85, v85, v234
	v_sub_f32_e32 v69, v69, v234
	v_exp_f32_e32 v85, v85
	v_exp_f32_e32 v69, v69
	v_sub_f32_e32 v86, v86, v234
	v_sub_f32_e32 v70, v70, v234
	v_exp_f32_e32 v86, v86
	v_exp_f32_e32 v70, v70
	v_sub_f32_e32 v87, v87, v234
	v_sub_f32_e32 v71, v71, v234
	v_exp_f32_e32 v87, v87
	v_exp_f32_e32 v71, v71
	v_add_f32_e32 v84, v68, v235
	v_add_f32_e32 v84, 0, v84
	v_add_f32_e32 v236, v69, v85
	v_add_f32_e32 v84, v236, v84
	v_add_f32_e32 v236, v70, v86
	v_add_f32_e32 v84, v236, v84
	v_add_f32_e32 v236, v71, v87
	v_sub_f32_e32 v88, v88, v234
	v_sub_f32_e32 v72, v72, v234
	v_add_f32_e32 v84, v236, v84
	v_exp_f32_e32 v88, v88
	v_exp_f32_e32 v236, v72
	v_sub_f32_e32 v73, v73, v234
	v_exp_f32_e32 v237, v73
	v_sub_f32_e32 v74, v74, v234
	v_add_f32_e32 v72, v236, v88
	v_add_f32_e32 v72, v72, v84
	v_sub_f32_e32 v84, v89, v234
	v_exp_f32_e32 v89, v84
	v_sub_f32_e32 v75, v75, v234
	v_exp_f32_e32 v75, v75
	v_sub_f32_e32 v76, v76, v234
	v_add_f32_e32 v73, v237, v89
	v_add_f32_e32 v72, v73, v72
	v_sub_f32_e32 v73, v90, v234
	v_exp_f32_e32 v73, v73
	v_exp_f32_e32 v90, v74
	v_sub_f32_e32 v77, v77, v234
	v_sub_f32_e32 v78, v78, v234
	v_sub_f32_e32 v79, v79, v234
	v_add_f32_e32 v74, v90, v73
	v_add_f32_e32 v72, v74, v72
	v_sub_f32_e32 v74, v91, v234
	v_exp_f32_e32 v74, v74
	v_sub_f32_e32 v80, v80, v234
	v_subrev_u32_e32 v231, 64, v231
	v_add_f32_e32 v84, v75, v74
	v_add_f32_e32 v72, v84, v72
	v_sub_f32_e32 v84, v92, v234
	v_exp_f32_e32 v91, v84
	v_exp_f32_e32 v92, v76
	v_cvt_pk_bf16_f32 v75, v90, v75
	v_add_f32_e32 v76, v92, v91
	v_add_f32_e32 v72, v76, v72
	v_sub_f32_e32 v76, v93, v234
	v_exp_f32_e32 v76, v76
	v_exp_f32_e32 v93, v77
	s_nop 0
	v_add_f32_e32 v77, v93, v76
	v_add_f32_e32 v72, v77, v72
	v_sub_f32_e32 v77, v94, v234
	v_exp_f32_e32 v77, v77
	v_exp_f32_e32 v94, v78
	v_cvt_pk_bf16_f32 v76, v91, v76
	v_add_f32_e32 v78, v94, v77
	v_add_f32_e32 v72, v78, v72
	v_sub_f32_e32 v78, v95, v234
	v_exp_f32_e32 v78, v78
	v_exp_f32_e32 v95, v79
	v_cvt_pk_bf16_f32 v77, v77, v78
	v_add_f32_e32 v79, v95, v78
	v_add_f32_e32 v72, v79, v72
	v_sub_f32_e32 v79, v96, v234
	v_exp_f32_e32 v79, v79
	v_exp_f32_e32 v96, v80
	s_nop 0
	v_add_f32_e32 v80, v96, v79
	v_add_f32_e32 v72, v80, v72
	v_sub_f32_e32 v80, v97, v234
	v_exp_f32_e32 v97, v80
	v_sub_f32_e32 v80, v81, v234
	v_exp_f32_e32 v238, v80
	v_cvt_pk_bf16_f32 v81, v86, v87
	v_cvt_pk_bf16_f32 v78, v79, v97
	v_add_f32_e32 v80, v238, v97
	v_add_f32_e32 v72, v80, v72
	v_sub_f32_e32 v80, v98, v234
	v_exp_f32_e32 v98, v80
	v_sub_f32_e32 v80, v82, v234
	v_exp_f32_e32 v239, v80
	v_cvt_pk_bf16_f32 v82, v88, v89
	v_add_f32_e32 v80, v239, v98
	v_add_f32_e32 v72, v80, v72
	v_sub_f32_e32 v80, v99, v234
	v_exp_f32_e32 v99, v80
	v_sub_f32_e32 v80, v83, v234
	v_exp_f32_e32 v234, v80
	v_cvt_pk_bf16_f32 v83, v73, v74
	v_cvt_pk_bf16_f32 v79, v98, v99
	v_cvt_pk_bf16_f32 v73, v70, v71
	v_add_f32_e32 v80, v234, v99
	v_add_f32_e32 v84, v80, v72
	v_cvt_pk_bf16_f32 v80, v235, v85
	v_add_u32_e32 v85, s90, v196
	v_add3_u32 v85, v85, v197, v198
	v_cvt_pk_bf16_f32 v72, v68, v69
	v_cvt_pk_bf16_f32 v68, v92, v93
	ds_read_b64_tr_b16 v[86:87], v85 offset:16384
	ds_read_b64_tr_b16 v[88:89], v85 offset:16896
	ds_read_b64_tr_b16 v[90:91], v85 offset:20480
	ds_read_b64_tr_b16 v[92:93], v85 offset:20992
	s_waitcnt lgkmcnt(0)
	v_mfma_f32_32x32x16_bf16 v[52:67], v[80:83], v[86:89], v[52:67]
	v_cvt_pk_bf16_f32 v74, v236, v237
	v_cvt_pk_bf16_f32 v69, v94, v95
	v_cvt_pk_bf16_f32 v70, v96, v238
	v_cvt_pk_bf16_f32 v71, v239, v234
	v_fmac_f32_e32 v84, v232, v233
	v_mfma_f32_32x32x16_bf16 v[36:51], v[80:83], v[90:93], v[36:51]
	ds_read_b64_tr_b16 v[86:87], v85 offset:17408
	ds_read_b64_tr_b16 v[88:89], v85 offset:17920
	ds_read_b64_tr_b16 v[90:91], v85 offset:21504
	ds_read_b64_tr_b16 v[92:93], v85 offset:22016
	s_waitcnt lgkmcnt(0)
	v_mfma_f32_32x32x16_bf16 v[52:67], v[76:79], v[86:89], v[52:67]
	v_mfma_f32_32x32x16_bf16 v[36:51], v[76:79], v[90:93], v[36:51]
	ds_read_b64_tr_b16 v[86:87], v85 offset:18432
	ds_read_b64_tr_b16 v[88:89], v85 offset:18944
	ds_read_b64_tr_b16 v[90:91], v85 offset:22528
	ds_read_b64_tr_b16 v[92:93], v85 offset:23040
	s_waitcnt lgkmcnt(0)
	v_mfma_f32_32x32x16_bf16 v[52:67], v[72:75], v[86:89], v[52:67]
	v_mfma_f32_32x32x16_bf16 v[36:51], v[72:75], v[90:93], v[36:51]
	ds_read_b64_tr_b16 v[86:87], v85 offset:19456
	ds_read_b64_tr_b16 v[88:89], v85 offset:19968
	ds_read_b64_tr_b16 v[90:91], v85 offset:23552
	ds_read_b64_tr_b16 v[92:93], v85 offset:24064
	v_add_u32_e32 v85, s14, v148
	v_sub_u32_e32 v239, v85, v193
	v_mov_b32_e32 v237, 0x3f803f80
	v_mov_b32_e32 v238, 0x3f800000
	s_waitcnt lgkmcnt(0)
; #define MFMA32(a, b, c) __builtin_amdgcn_mfma_f32_32x32x16_bf16((a), (b), (c), 0, 0, 0)
; template <bool CMP> DI void tile_compute(LAS unsigned char* lds, int buf, const bf16x8 (&q)[4], int lo, int hv, ASt& st, f32x16& imp0, f32x16& imp1, int jt, LAS float* wsf, int lane) {
;     ...
;     if (CMP) {
; #pragma unroll
;         for (int s = 0; s < 4; ++s) {
;             bf16x8 w0, w1;
; #pragma unroll
;             for (int j = 0; j < 8; ++j) { const int jj = 64 * jt + 16 * s + 8 * (j >> 2) + 4 * hi + (j & 3);
;                 const int n0 = r, n1 = 32 + r;
;                 w0[j] = (jj >= 4 * n0 - 1 && jj <= 4 * n0 + 3) ? (short)0x3F80 : (short)0;
;                 w1[j] = (jj >= 4 * n1 - 1 && jj <= 4 * n1 + 3) ? (short)0x3F80 : (short)0; }
;             imp0 = MFMA32(pa[s], w0, imp0); imp1 = MFMA32(pa[s], w1, imp1); asm volatile("" ::: "memory");
;         }
;     }
	v_mfma_f32_32x32x16_bf16 v[52:67], v[68:71], v[86:89], v[52:67]
	v_mfma_f32_32x32x16_bf16 v[36:51], v[68:71], v[90:93], v[36:51]
	s_add_i32 s14, s14, 64
	v_add_u32_e32 v236, 0xffffff80, v239
	v_cmp_eq_u32_e32 vcc, -4, v236
	s_nop 1
	v_cndmask_b32_e32 v241, 0, v238, vcc
	v_cmp_eq_u32_e32 vcc, 0, v236
	s_nop 1
	v_cndmask_b32_e32 v240, 0, v237, vcc
	v_cndmask_b32_e32 v241, v241, v237, vcc
	v_cmp_eq_u32_e32 vcc, -12, v236
	s_nop 1
	v_cndmask_b32_e32 v243, 0, v238, vcc
	v_cmp_eq_u32_e32 vcc, -8, v236
	s_nop 1
	v_cndmask_b32_e32 v242, 0, v237, vcc
	v_cndmask_b32_e32 v243, v243, v237, vcc
	v_add_u32_e32 v235, 0, v239
	v_cmp_eq_u32_e32 vcc, -4, v235
	s_nop 1
	v_cndmask_b32_e32 v87, 0, v238, vcc
	v_cmp_eq_u32_e32 vcc, 0, v235
	s_nop 1
	v_cndmask_b32_e32 v86, 0, v237, vcc
	v_cndmask_b32_e32 v87, v87, v237, vcc
	v_cmp_eq_u32_e32 vcc, -12, v235
	s_nop 1
	v_cndmask_b32_e32 v89, 0, v238, vcc
	v_cmp_eq_u32_e32 vcc, -8, v235
	s_nop 1
	v_cndmask_b32_e32 v88, 0, v237, vcc
	v_cndmask_b32_e32 v89, v89, v237, vcc
	s_nop 7
	v_mfma_f32_32x32x16_bf16 v[20:35], v[80:83], v[86:89], v[20:35]
	v_mfma_f32_32x32x16_bf16 v[4:19], v[80:83], v[240:243], v[4:19]
	v_add_u32_e32 v236, 0xffffff90, v239
	v_cmp_eq_u32_e32 vcc, -4, v236
	s_nop 1
	v_cndmask_b32_e32 v245, 0, v238, vcc
	v_cmp_eq_u32_e32 vcc, 0, v236
	s_nop 1
	v_cndmask_b32_e32 v244, 0, v237, vcc
	v_cndmask_b32_e32 v245, v245, v237, vcc
	v_cmp_eq_u32_e32 vcc, -12, v236
	s_nop 1
	v_cndmask_b32_e32 v247, 0, v238, vcc
	v_cmp_eq_u32_e32 vcc, -8, v236
	s_nop 1
	v_cndmask_b32_e32 v246, 0, v237, vcc
	v_cndmask_b32_e32 v247, v247, v237, vcc
	v_add_u32_e32 v235, 16, v239
	v_cmp_eq_u32_e32 vcc, -4, v235
	s_nop 1
	v_cndmask_b32_e32 v81, 0, v238, vcc
	v_cmp_eq_u32_e32 vcc, 0, v235
	s_nop 1
	v_cndmask_b32_e32 v80, 0, v237, vcc
	v_cndmask_b32_e32 v81, v81, v237, vcc
	v_cmp_eq_u32_e32 vcc, -12, v235
	s_nop 1
	v_cndmask_b32_e32 v83, 0, v238, vcc
	v_cmp_eq_u32_e32 vcc, -8, v235
	s_nop 1
	v_cndmask_b32_e32 v82, 0, v237, vcc
	v_cndmask_b32_e32 v83, v83, v237, vcc
	s_nop 7
	v_mfma_f32_32x32x16_bf16 v[20:35], v[76:79], v[80:83], v[20:35]
	v_mfma_f32_32x32x16_bf16 v[4:19], v[76:79], v[244:247], v[4:19]
	v_add_u32_e32 v236, 0xffffffa0, v239
	v_cmp_eq_u32_e32 vcc, -4, v236
	s_nop 1
	v_cndmask_b32_e32 v241, 0, v238, vcc
	v_cmp_eq_u32_e32 vcc, 0, v236
	s_nop 1
	v_cndmask_b32_e32 v240, 0, v237, vcc
	v_cndmask_b32_e32 v241, v241, v237, vcc
	v_cmp_eq_u32_e32 vcc, -12, v236
	s_nop 1
	v_cndmask_b32_e32 v243, 0, v238, vcc
	v_cmp_eq_u32_e32 vcc, -8, v236
	s_nop 1
	v_cndmask_b32_e32 v242, 0, v237, vcc
	v_cndmask_b32_e32 v243, v243, v237, vcc
	v_add_u32_e32 v235, 32, v239
	v_cmp_eq_u32_e32 vcc, -4, v235
	s_nop 1
	v_cndmask_b32_e32 v77, 0, v238, vcc
	v_cmp_eq_u32_e32 vcc, 0, v235
	s_nop 1
	v_cndmask_b32_e32 v76, 0, v237, vcc
	v_cndmask_b32_e32 v77, v77, v237, vcc
	v_cmp_eq_u32_e32 vcc, -12, v235
	s_nop 1
	v_cndmask_b32_e32 v79, 0, v238, vcc
	v_cmp_eq_u32_e32 vcc, -8, v235
	s_nop 1
	v_cndmask_b32_e32 v78, 0, v237, vcc
	v_cndmask_b32_e32 v79, v79, v237, vcc
	s_nop 7
	v_mfma_f32_32x32x16_bf16 v[20:35], v[72:75], v[76:79], v[20:35]
	v_mfma_f32_32x32x16_bf16 v[4:19], v[72:75], v[240:243], v[4:19]
	s_add_u32 s88, s88, 0x2000
	s_addc_u32 s89, s89, 0
	v_add_u32_e32 v236, 0xffffffb0, v239
	v_cmp_eq_u32_e32 vcc, -4, v236
	s_nop 1
	v_cndmask_b32_e32 v245, 0, v238, vcc
	v_cmp_eq_u32_e32 vcc, 0, v236
	s_nop 1
	v_cndmask_b32_e32 v244, 0, v237, vcc
	v_cndmask_b32_e32 v245, v245, v237, vcc
	v_cmp_eq_u32_e32 vcc, -12, v236
	s_nop 1
	v_cndmask_b32_e32 v247, 0, v238, vcc
	v_cmp_eq_u32_e32 vcc, -8, v236
	s_nop 1
	v_cndmask_b32_e32 v246, 0, v237, vcc
	v_cndmask_b32_e32 v247, v247, v237, vcc
	v_add_u32_e32 v235, 48, v239
	v_cmp_eq_u32_e32 vcc, -4, v235
	s_nop 1
	v_cndmask_b32_e32 v73, 0, v238, vcc
	v_cmp_eq_u32_e32 vcc, 0, v235
	s_nop 1
	v_cndmask_b32_e32 v72, 0, v237, vcc
	v_cndmask_b32_e32 v73, v73, v237, vcc
	v_cmp_eq_u32_e32 vcc, -12, v235
	s_nop 1
	v_cndmask_b32_e32 v75, 0, v238, vcc
	v_cmp_eq_u32_e32 vcc, -8, v235
	s_nop 1
	v_cndmask_b32_e32 v74, 0, v237, vcc
	v_cndmask_b32_e32 v75, v75, v237, vcc
	s_nop 7
	v_mfma_f32_32x32x16_bf16 v[20:35], v[68:71], v[72:75], v[20:35]
	s_add_i32 s3, s3, 1
	s_cmp_eq_u32 s84, s14
	v_mfma_f32_32x32x16_bf16 v[4:19], v[68:71], v[244:247], v[4:19]
	s_cbranch_scc1 .LBB0_557
	v_mov_b32_e32 v232, v84
	v_mov_b32_e32 v233, v141
	s_branch .LBB0_547

; #define LAS __attribute__((address_space(3)))
; #define LDS_WAIT() asm volatile("s_waitcnt lgkmcnt(0)" ::: "memory")
; #define MFMA32(a, b, c) __builtin_amdgcn_mfma_f32_32x32x16_bf16((a), (b), (c), 0, 0, 0)
; DI s16x4 vtr(const LAS unsigned char* p) { return __builtin_bit_cast(s16x4, __builtin_amdgcn_ds_read_tr16_b64_v4i16((LAS v4i16_t*)p)); }
; DI bf16x8 cat8(s16x4 lo, s16x4 hi) { return __builtin_shufflevector(lo, hi, 0, 1, 2, 3, 4, 5, 6, 7); }
; template <bool CMP> DI void tile_compute(LAS unsigned char* lds, int buf, const bf16x8 (&q)[4], int lo, int hv, ASt& st, f32x16& imp0, f32x16& imp1, int jt, LAS float* wsf, int lane) {
;     ...
;     const float msub = (!anyPart && dead) ? 1e30f : mnew;
; #pragma unroll
;     for (int rg = 0; rg < 16; ++rg) { p0[rg] = __builtin_amdgcn_exp2f(p0[rg] - msub); p1[rg] = __builtin_amdgcn_exp2f(p1[rg] - msub); sum += p0[rg] + p1[rg]; }
;     st.l = st.l * alpha + sum;
;     if (__builtin_amdgcn_ballot_w64(alpha != 1.f) != 0ull) {
;         if (hi == 0) wsf[r] = alpha;
;         LDS_WAIT();
; #pragma unroll
;         for (int g4 = 0; g4 < 4; ++g4) { const f32x4 f = *(const LAS f32x4*)(wsf + 8 * g4 + 4 * hi);
; #pragma unroll
;             for (int k = 0; k < 4; ++k) { st.o0[4 * g4 + k] *= f[k]; st.o1[4 * g4 + k] *= f[k]; if (CMP) { imp0[4 * g4 + k] *= f[k]; imp1[4 * g4 + k] *= f[k]; } } }
;         LDS_WAIT();
;     }
;     bf16x8 pa[4];
;     pa[0] = pack8(p0[0], p0[1], p0[2], p0[3], p0[4], p0[5], p0[6], p0[7]); pa[1] = pack8(p0[8], p0[9], p0[10], p0[11], p0[12], p0[13], p0[14], p0[15]);
;     pa[2] = pack8(p1[0], p1[1], p1[2], p1[3], p1[4], p1[5], p1[6], p1[7]); pa[3] = pack8(p1[8], p1[9], p1[10], p1[11], p1[12], p1[13], p1[14], p1[15]);
;     const LAS unsigned char* vb = lds + A_VT + buf * 8192 + (4 * hi + ((lane & 15) >> 2)) * 64 + ((lane >> 4) & 1) * 32 + (lane & 3) * 8;
; #pragma unroll
;     for (int s = 0; s < 4; ++s) {
;         const bf16x8 v0 = cat8(vtr(vb + s * 1024), vtr(vb + s * 1024 + 512));
;         const bf16x8 v1 = cat8(vtr(vb + 4096 + s * 1024), vtr(vb + 4096 + s * 1024 + 512));
;         st.o0 = MFMA32(pa[s], v0, st.o0); st.o1 = MFMA32(pa[s], v1, st.o1);
;     }
.LBB0_1168:
	v_cndmask_b32_e64 v229, v141, v218, s[80:81]
	v_sub_f32_e32 v84, v84, v229
	v_sub_f32_e32 v68, v68, v229
	v_exp_f32_e32 v230, v84
	v_exp_f32_e32 v68, v68
	v_sub_f32_e32 v85, v85, v229
	v_sub_f32_e32 v69, v69, v229
	v_exp_f32_e32 v85, v85
	v_exp_f32_e32 v69, v69
	v_sub_f32_e32 v86, v86, v229
	v_sub_f32_e32 v70, v70, v229
	v_exp_f32_e32 v86, v86
	v_exp_f32_e32 v70, v70
	v_sub_f32_e32 v87, v87, v229
	v_sub_f32_e32 v71, v71, v229
	v_exp_f32_e32 v87, v87
	v_exp_f32_e32 v71, v71
	v_add_f32_e32 v84, v68, v230
	v_add_f32_e32 v84, 0, v84
	v_add_f32_e32 v231, v69, v85
	v_add_f32_e32 v84, v231, v84
	v_add_f32_e32 v231, v70, v86
	v_add_f32_e32 v84, v231, v84
	v_add_f32_e32 v231, v71, v87
	v_sub_f32_e32 v88, v88, v229
	v_sub_f32_e32 v72, v72, v229
	v_add_f32_e32 v84, v231, v84
	v_exp_f32_e32 v88, v88
	v_exp_f32_e32 v231, v72
	v_sub_f32_e32 v73, v73, v229
	v_exp_f32_e32 v232, v73
	v_sub_f32_e32 v74, v74, v229
	v_add_f32_e32 v72, v231, v88
	v_add_f32_e32 v72, v72, v84
	v_sub_f32_e32 v84, v89, v229
	v_exp_f32_e32 v89, v84
	v_sub_f32_e32 v75, v75, v229
	v_exp_f32_e32 v75, v75
	v_sub_f32_e32 v76, v76, v229
	v_add_f32_e32 v73, v232, v89
	v_add_f32_e32 v72, v73, v72
	v_sub_f32_e32 v73, v90, v229
	v_exp_f32_e32 v73, v73
	v_exp_f32_e32 v90, v74
	v_sub_f32_e32 v77, v77, v229
	v_sub_f32_e32 v78, v78, v229
	v_sub_f32_e32 v79, v79, v229
	v_add_f32_e32 v74, v90, v73
	v_add_f32_e32 v72, v74, v72
	v_sub_f32_e32 v74, v91, v229
	v_exp_f32_e32 v74, v74
	v_sub_f32_e32 v80, v80, v229
	v_subrev_u32_e32 v226, 64, v226
	v_add_f32_e32 v84, v75, v74
	v_add_f32_e32 v72, v84, v72
	v_sub_f32_e32 v84, v92, v229
	v_exp_f32_e32 v91, v84
	v_exp_f32_e32 v92, v76
	v_cvt_pk_bf16_f32 v75, v90, v75
	v_add_f32_e32 v76, v92, v91
	v_add_f32_e32 v72, v76, v72
	v_sub_f32_e32 v76, v93, v229
	v_exp_f32_e32 v76, v76
	v_exp_f32_e32 v93, v77
	s_nop 0
	v_add_f32_e32 v77, v93, v76
	v_add_f32_e32 v72, v77, v72
	v_sub_f32_e32 v77, v94, v229
	v_exp_f32_e32 v77, v77
	v_exp_f32_e32 v94, v78
	v_cvt_pk_bf16_f32 v76, v91, v76
	v_add_f32_e32 v78, v94, v77
	v_add_f32_e32 v72, v78, v72
	v_sub_f32_e32 v78, v95, v229
	v_exp_f32_e32 v78, v78
	v_exp_f32_e32 v95, v79
	v_cvt_pk_bf16_f32 v77, v77, v78
	v_add_f32_e32 v79, v95, v78
	v_add_f32_e32 v72, v79, v72
	v_sub_f32_e32 v79, v96, v229
	v_exp_f32_e32 v79, v79
	v_exp_f32_e32 v96, v80
	s_nop 0
	v_add_f32_e32 v80, v96, v79
	v_add_f32_e32 v72, v80, v72
	v_sub_f32_e32 v80, v97, v229
	v_exp_f32_e32 v97, v80
	v_sub_f32_e32 v80, v81, v229
	v_exp_f32_e32 v233, v80
	v_cvt_pk_bf16_f32 v81, v86, v87
	v_cvt_pk_bf16_f32 v78, v79, v97
	v_add_f32_e32 v80, v233, v97
	v_add_f32_e32 v72, v80, v72
	v_sub_f32_e32 v80, v98, v229
	v_exp_f32_e32 v98, v80
	v_sub_f32_e32 v80, v82, v229
	v_exp_f32_e32 v234, v80
	v_cvt_pk_bf16_f32 v82, v88, v89
	v_add_f32_e32 v80, v234, v98
	v_add_f32_e32 v72, v80, v72
	v_sub_f32_e32 v80, v99, v229
	v_exp_f32_e32 v99, v80
	v_sub_f32_e32 v80, v83, v229
	v_exp_f32_e32 v229, v80
	v_cvt_pk_bf16_f32 v83, v73, v74
	v_cvt_pk_bf16_f32 v79, v98, v99
	v_cvt_pk_bf16_f32 v73, v70, v71
	v_add_f32_e32 v80, v229, v99
	v_add_f32_e32 v84, v80, v72
	v_cvt_pk_bf16_f32 v80, v230, v85
	v_add_u32_e32 v85, s28, v188
	v_add3_u32 v85, v85, v187, v186
	v_cvt_pk_bf16_f32 v72, v68, v69
	v_cvt_pk_bf16_f32 v68, v92, v93
	ds_read_b64_tr_b16 v[86:87], v85 offset:16384
	ds_read_b64_tr_b16 v[88:89], v85 offset:16896
	ds_read_b64_tr_b16 v[90:91], v85 offset:20480
	ds_read_b64_tr_b16 v[92:93], v85 offset:20992
	s_waitcnt lgkmcnt(0)
	v_mfma_f32_32x32x16_bf16 v[52:67], v[80:83], v[86:89], v[52:67]
	v_cvt_pk_bf16_f32 v74, v231, v232
	v_cvt_pk_bf16_f32 v69, v94, v95
	v_cvt_pk_bf16_f32 v70, v96, v233
	v_cvt_pk_bf16_f32 v71, v234, v229
	v_fmac_f32_e32 v84, v227, v228
	v_mfma_f32_32x32x16_bf16 v[36:51], v[80:83], v[90:93], v[36:51]
	ds_read_b64_tr_b16 v[86:87], v85 offset:17408
	ds_read_b64_tr_b16 v[88:89], v85 offset:17920
	ds_read_b64_tr_b16 v[90:91], v85 offset:21504
	ds_read_b64_tr_b16 v[92:93], v85 offset:22016
	s_waitcnt lgkmcnt(0)
	v_mfma_f32_32x32x16_bf16 v[52:67], v[76:79], v[86:89], v[52:67]
	v_mfma_f32_32x32x16_bf16 v[36:51], v[76:79], v[90:93], v[36:51]
	ds_read_b64_tr_b16 v[86:87], v85 offset:18432
	ds_read_b64_tr_b16 v[88:89], v85 offset:18944
	ds_read_b64_tr_b16 v[90:91], v85 offset:22528
	ds_read_b64_tr_b16 v[92:93], v85 offset:23040
	s_waitcnt lgkmcnt(0)
	v_mfma_f32_32x32x16_bf16 v[52:67], v[72:75], v[86:89], v[52:67]
	v_mfma_f32_32x32x16_bf16 v[36:51], v[72:75], v[90:93], v[36:51]
	ds_read_b64_tr_b16 v[86:87], v85 offset:19456
	ds_read_b64_tr_b16 v[88:89], v85 offset:19968
	ds_read_b64_tr_b16 v[90:91], v85 offset:23552
	ds_read_b64_tr_b16 v[92:93], v85 offset:24064
	v_add_u32_e32 v85, s16, v148
	v_sub_u32_e32 v239, v85, v196
	v_mov_b32_e32 v237, 0x3f803f80
	v_mov_b32_e32 v238, 0x3f800000
	s_waitcnt lgkmcnt(0)
; #define MFMA32(a, b, c) __builtin_amdgcn_mfma_f32_32x32x16_bf16((a), (b), (c), 0, 0, 0)
; template <bool CMP> DI void tile_compute(LAS unsigned char* lds, int buf, const bf16x8 (&q)[4], int lo, int hv, ASt& st, f32x16& imp0, f32x16& imp1, int jt, LAS float* wsf, int lane) {
;     ...
;     if (CMP) {
; #pragma unroll
;         for (int s = 0; s < 4; ++s) {
;             bf16x8 w0, w1;
; #pragma unroll
;             for (int j = 0; j < 8; ++j) { const int jj = 64 * jt + 16 * s + 8 * (j >> 2) + 4 * hi + (j & 3);
;                 const int n0 = r, n1 = 32 + r;
;                 w0[j] = (jj >= 4 * n0 - 1 && jj <= 4 * n0 + 3) ? (short)0x3F80 : (short)0;
;                 w1[j] = (jj >= 4 * n1 - 1 && jj <= 4 * n1 + 3) ? (short)0x3F80 : (short)0; }
;             imp0 = MFMA32(pa[s], w0, imp0); imp1 = MFMA32(pa[s], w1, imp1); asm volatile("" ::: "memory");
;         }
;     }
	v_mfma_f32_32x32x16_bf16 v[52:67], v[68:71], v[86:89], v[52:67]
	v_mfma_f32_32x32x16_bf16 v[36:51], v[68:71], v[90:93], v[36:51]
	s_add_i32 s16, s16, 64
	v_add_u32_e32 v236, 0xffffff80, v239
	v_cmp_eq_u32_e32 vcc, -4, v236
	s_nop 1
	v_cndmask_b32_e32 v241, 0, v238, vcc
	v_cmp_eq_u32_e32 vcc, 0, v236
	s_nop 1
	v_cndmask_b32_e32 v240, 0, v237, vcc
	v_cndmask_b32_e32 v241, v241, v237, vcc
	v_cmp_eq_u32_e32 vcc, -12, v236
	s_nop 1
	v_cndmask_b32_e32 v243, 0, v238, vcc
	v_cmp_eq_u32_e32 vcc, -8, v236
	s_nop 1
	v_cndmask_b32_e32 v242, 0, v237, vcc
	v_cndmask_b32_e32 v243, v243, v237, vcc
	v_add_u32_e32 v235, 0, v239
	v_cmp_eq_u32_e32 vcc, -4, v235
	s_nop 1
	v_cndmask_b32_e32 v87, 0, v238, vcc
	v_cmp_eq_u32_e32 vcc, 0, v235
	s_nop 1
	v_cndmask_b32_e32 v86, 0, v237, vcc
	v_cndmask_b32_e32 v87, v87, v237, vcc
	v_cmp_eq_u32_e32 vcc, -12, v235
	s_nop 1
	v_cndmask_b32_e32 v89, 0, v238, vcc
	v_cmp_eq_u32_e32 vcc, -8, v235
	s_nop 1
	v_cndmask_b32_e32 v88, 0, v237, vcc
	v_cndmask_b32_e32 v89, v89, v237, vcc
	s_nop 7
	v_mfma_f32_32x32x16_bf16 v[20:35], v[80:83], v[86:89], v[20:35]
	v_mfma_f32_32x32x16_bf16 v[4:19], v[80:83], v[240:243], v[4:19]
	v_add_u32_e32 v236, 0xffffff90, v239
	v_cmp_eq_u32_e32 vcc, -4, v236
	s_nop 1
	v_cndmask_b32_e32 v245, 0, v238, vcc
	v_cmp_eq_u32_e32 vcc, 0, v236
	s_nop 1
	v_cndmask_b32_e32 v244, 0, v237, vcc
	v_cndmask_b32_e32 v245, v245, v237, vcc
	v_cmp_eq_u32_e32 vcc, -12, v236
	s_nop 1
	v_cndmask_b32_e32 v247, 0, v238, vcc
	v_cmp_eq_u32_e32 vcc, -8, v236
	s_nop 1
	v_cndmask_b32_e32 v246, 0, v237, vcc
	v_cndmask_b32_e32 v247, v247, v237, vcc
	v_add_u32_e32 v235, 16, v239
	v_cmp_eq_u32_e32 vcc, -4, v235
	s_nop 1
	v_cndmask_b32_e32 v81, 0, v238, vcc
	v_cmp_eq_u32_e32 vcc, 0, v235
	s_nop 1
	v_cndmask_b32_e32 v80, 0, v237, vcc
	v_cndmask_b32_e32 v81, v81, v237, vcc
	v_cmp_eq_u32_e32 vcc, -12, v235
	s_nop 1
	v_cndmask_b32_e32 v83, 0, v238, vcc
	v_cmp_eq_u32_e32 vcc, -8, v235
	s_nop 1
	v_cndmask_b32_e32 v82, 0, v237, vcc
	v_cndmask_b32_e32 v83, v83, v237, vcc
	s_nop 7
	v_mfma_f32_32x32x16_bf16 v[20:35], v[76:79], v[80:83], v[20:35]
	v_mfma_f32_32x32x16_bf16 v[4:19], v[76:79], v[244:247], v[4:19]
	v_add_u32_e32 v236, 0xffffffa0, v239
	v_cmp_eq_u32_e32 vcc, -4, v236
	s_nop 1
	v_cndmask_b32_e32 v241, 0, v238, vcc
	v_cmp_eq_u32_e32 vcc, 0, v236
	s_nop 1
	v_cndmask_b32_e32 v240, 0, v237, vcc
	v_cndmask_b32_e32 v241, v241, v237, vcc
	v_cmp_eq_u32_e32 vcc, -12, v236
	s_nop 1
	v_cndmask_b32_e32 v243, 0, v238, vcc
	v_cmp_eq_u32_e32 vcc, -8, v236
	s_nop 1
	v_cndmask_b32_e32 v242, 0, v237, vcc
	v_cndmask_b32_e32 v243, v243, v237, vcc
	v_add_u32_e32 v235, 32, v239
	v_cmp_eq_u32_e32 vcc, -4, v235
	s_nop 1
	v_cndmask_b32_e32 v77, 0, v238, vcc
	v_cmp_eq_u32_e32 vcc, 0, v235
	s_nop 1
	v_cndmask_b32_e32 v76, 0, v237, vcc
	v_cndmask_b32_e32 v77, v77, v237, vcc
	v_cmp_eq_u32_e32 vcc, -12, v235
	s_nop 1
	v_cndmask_b32_e32 v79, 0, v238, vcc
	v_cmp_eq_u32_e32 vcc, -8, v235
	s_nop 1
	v_cndmask_b32_e32 v78, 0, v237, vcc
	v_cndmask_b32_e32 v79, v79, v237, vcc
	s_nop 7
	v_mfma_f32_32x32x16_bf16 v[20:35], v[72:75], v[76:79], v[20:35]
	v_mfma_f32_32x32x16_bf16 v[4:19], v[72:75], v[240:243], v[4:19]
	s_add_u32 s88, s88, 0x2000
	s_addc_u32 s89, s89, 0
	v_add_u32_e32 v236, 0xffffffb0, v239
	v_cmp_eq_u32_e32 vcc, -4, v236
	s_nop 1
	v_cndmask_b32_e32 v245, 0, v238, vcc
	v_cmp_eq_u32_e32 vcc, 0, v236
	s_nop 1
	v_cndmask_b32_e32 v244, 0, v237, vcc
	v_cndmask_b32_e32 v245, v245, v237, vcc
	v_cmp_eq_u32_e32 vcc, -12, v236
	s_nop 1
	v_cndmask_b32_e32 v247, 0, v238, vcc
	v_cmp_eq_u32_e32 vcc, -8, v236
	s_nop 1
	v_cndmask_b32_e32 v246, 0, v237, vcc
	v_cndmask_b32_e32 v247, v247, v237, vcc
	v_add_u32_e32 v235, 48, v239
	v_cmp_eq_u32_e32 vcc, -4, v235
	s_nop 1
	v_cndmask_b32_e32 v73, 0, v238, vcc
	v_cmp_eq_u32_e32 vcc, 0, v235
	s_nop 1
	v_cndmask_b32_e32 v72, 0, v237, vcc
	v_cndmask_b32_e32 v73, v73, v237, vcc
	v_cmp_eq_u32_e32 vcc, -12, v235
	s_nop 1
	v_cndmask_b32_e32 v75, 0, v238, vcc
	v_cmp_eq_u32_e32 vcc, -8, v235
	s_nop 1
	v_cndmask_b32_e32 v74, 0, v237, vcc
	v_cndmask_b32_e32 v75, v75, v237, vcc
	s_nop 7
	v_mfma_f32_32x32x16_bf16 v[20:35], v[68:71], v[72:75], v[20:35]
	s_add_i32 s6, s6, 1
	s_cmp_eq_u32 s90, s16
	v_mfma_f32_32x32x16_bf16 v[4:19], v[68:71], v[244:247], v[4:19]
	s_cbranch_scc1 .LBB0_1170
	v_mov_b32_e32 v227, v84
	v_mov_b32_e32 v228, v141
	s_branch .LBB0_1160
